# up-proj (conv-gate) epilogue: the value-branch weight wait no longer drains the just-issued m=0 activation store (vmcnt(1) instead of vmcnt(0); the never-taken exec-skip path keeps a full wait)
# speedup vs baseline: 1.1126x; 1.0943x over previous
.LBB0_115:
	s_or_b64 exec, exec, s[0:1]
	v_cmp_eq_u32_e64 s[42:43], 0, v183
	v_cndmask_b32_e32 v159, v205, v244, vcc
	v_cndmask_b32_e32 v158, v204, v240, vcc
	v_cndmask_b32_e64 v157, v245, v207, s[42:43]
	v_cndmask_b32_e64 v156, v241, v206, s[42:43]
	s_waitcnt vmcnt(4)
	v_pk_fma_f32 v[158:159], v[122:123], v[158:159], v[134:135]
	v_cndmask_b32_e32 v173, v201, v233, vcc
	v_cndmask_b32_e32 v172, v200, v228, vcc
	v_pk_fma_f32 v[156:157], v[126:127], v[156:157], v[158:159]
	v_cndmask_b32_e64 v171, v235, v203, s[42:43]
	v_cndmask_b32_e64 v170, v229, v202, s[42:43]
	v_pk_fma_f32 v[172:173], v[124:125], v[172:173], v[136:137]
	v_pk_fma_f32 v[156:157], v[186:187], v[130:131], v[156:157]
	v_pk_fma_f32 v[170:171], v[128:129], v[170:171], v[172:173]
	v_cndmask_b32_e32 v187, v244, v237, vcc
	v_cndmask_b32_e32 v186, v240, v231, vcc
	v_pk_fma_f32 v[170:171], v[184:185], v[132:133], v[170:171]
	v_cndmask_b32_e64 v185, v239, v245, s[42:43]
	v_cndmask_b32_e64 v184, v234, v241, s[42:43]
	v_pk_fma_f32 v[186:187], v[122:123], v[186:187], v[134:135]
	v_cndmask_b32_e32 v201, v233, v213, vcc
	v_pk_fma_f32 v[184:185], v[126:127], v[184:185], v[186:187]
	v_cndmask_b32_e32 v200, v228, v0, vcc
	v_pk_fma_f32 v[184:185], v[198:199], v[130:131], v[184:185]
	v_cndmask_b32_e64 v199, v227, v235, s[42:43]
	v_cndmask_b32_e64 v198, v151, v229, s[42:43]
	v_pk_fma_f32 v[200:201], v[124:125], v[200:201], v[136:137]
	v_cndmask_b32_e32 v203, v237, v246, vcc
	v_cndmask_b32_e32 v202, v231, v242, vcc
	v_pk_fma_f32 v[198:199], v[128:129], v[198:199], v[200:201]
	v_cndmask_b32_e64 v201, v247, v239, s[42:43]
	v_cndmask_b32_e64 v200, v243, v234, s[42:43]
	v_pk_fma_f32 v[122:123], v[122:123], v[202:203], v[134:135]
	v_cndmask_b32_e32 v135, v213, v236, vcc
	v_pk_fma_f32 v[122:123], v[126:127], v[200:201], v[122:123]
	v_cndmask_b32_e32 v134, v0, v230, vcc
	v_mul_f32_e32 v158, 0xbfb8aa3b, v156
	v_mul_f32_e32 v159, 0xbfb8aa3b, v157
	v_mul_f32_e32 v172, 0xbfb8aa3b, v170
	v_mul_f32_e32 v173, 0xbfb8aa3b, v171
	v_pk_fma_f32 v[122:123], v[176:177], v[130:131], v[122:123]
	v_cndmask_b32_e64 v131, v238, v227, s[42:43]
	v_cndmask_b32_e64 v130, v232, v151, s[42:43]
	v_pk_fma_f32 v[124:125], v[124:125], v[134:135], v[136:137]
	v_exp_f32_e32 v158, v158
	v_exp_f32_e32 v159, v159
	v_exp_f32_e32 v172, v172
	v_exp_f32_e32 v173, v173
	v_pk_fma_f32 v[124:125], v[128:129], v[130:131], v[124:125]
	v_mov_b32_e32 v179, v178
	v_pk_fma_f32 v[124:125], v[174:175], v[132:133], v[124:125]
	v_mov_b32_e32 v183, v182
	v_mul_f32_e32 v0, 0xbfb8aa3b, v124
	v_exp_f32_e32 v0, v0
	v_mul_f32_e32 v128, 0xbfb8aa3b, v125
	v_mov_b32_e32 v130, v178
	v_mov_b32_e32 v131, v178
	v_add_f32_e32 v158, 1.0, v158
	v_add_f32_e32 v159, 1.0, v159
	v_add_f32_e32 v172, 1.0, v172
	v_add_f32_e32 v173, 1.0, v173
	v_exp_f32_e32 v129, v128
	v_pk_mul_f32 v[104:105], v[104:105], v[130:131]
	v_pk_mul_f32 v[102:103], v[102:103], v[178:179]
	v_pk_mul_f32 v[98:99], v[98:99], v[182:183]
	v_mov_b32_e32 v177, v1
	v_mov_b32_e32 v179, v1
	v_mov_b32_e32 v183, v1
	v_mov_b32_e32 v201, v1
	v_rcp_f32_e32 v158, v158
	v_rcp_f32_e32 v159, v159
	v_rcp_f32_e32 v172, v172
	v_rcp_f32_e32 v173, v173
	v_mov_b32_e32 v130, v182
	v_mov_b32_e32 v131, v182
	v_mov_b32_e32 v176, v1
	v_mov_b32_dpp v177, v102 row_ror:2 row_mask:0xf bank_mask:0xf
	v_mov_b32_e32 v178, v1
	v_mov_b32_dpp v179, v103 row_ror:2 row_mask:0xf bank_mask:0xf
	v_mov_b32_e32 v182, v1
	v_mov_b32_dpp v183, v104 row_ror:2 row_mask:0xf bank_mask:0xf
	v_mov_b32_e32 v200, v1
	v_mov_b32_dpp v201, v105 row_ror:2 row_mask:0xf bank_mask:0xf
	v_pk_fma_f32 v[188:189], v[188:189], v[132:133], v[198:199]
	v_pk_mul_f32 v[100:101], v[100:101], v[130:131]
	v_mov_b32_dpp v176, v102 row_ror:1 row_mask:0xf bank_mask:0xf
	v_mov_b32_dpp v178, v103 row_ror:1 row_mask:0xf bank_mask:0xf
	v_mov_b32_dpp v182, v104 row_ror:1 row_mask:0xf bank_mask:0xf
	v_mov_b32_dpp v200, v105 row_ror:1 row_mask:0xf bank_mask:0xf
	v_cndmask_b32_e32 v130, v194, v177, vcc
	v_cndmask_b32_e32 v131, v195, v179, vcc
	v_cndmask_b32_e32 v132, v196, v183, vcc
	v_cndmask_b32_e32 v133, v197, v201, vcc
	v_mul_f32_e32 v186, 0xbfb8aa3b, v184
	v_mul_f32_e32 v187, 0xbfb8aa3b, v185
	v_mul_f32_e32 v198, 0xbfb8aa3b, v188
	v_mul_f32_e32 v199, 0xbfb8aa3b, v189
	v_add_f32_e32 v0, 1.0, v0
	v_cndmask_b32_e64 v134, v176, v190, s[42:43]
	v_cndmask_b32_e64 v135, v178, v191, s[42:43]
	v_cndmask_b32_e64 v136, v182, v192, s[42:43]
	v_cndmask_b32_e64 v137, v200, v193, s[42:43]
	s_waitcnt vmcnt(1)
	v_pk_fma_f32 v[132:133], v[116:117], v[132:133], v[120:121]
	v_pk_fma_f32 v[130:131], v[114:115], v[130:131], v[118:119]
	v_exp_f32_e32 v186, v186
	v_exp_f32_e32 v187, v187
	v_exp_f32_e32 v198, v198
	v_exp_f32_e32 v199, v199
	v_rcp_f32_e32 v128, v0
	v_add_f32_e32 v0, 1.0, v129
	v_pk_fma_f32 v[132:133], v[112:113], v[136:137], v[132:133]
	v_pk_fma_f32 v[130:131], v[110:111], v[134:135], v[130:131]
	v_rcp_f32_e32 v129, v0
	v_or_b32_e32 v0, 16, v150
	v_or_b32_e32 v174, 32, v150
	v_or_b32_e32 v175, 48, v150
	v_pk_mul_f32 v[150:151], v[156:157], v[158:159]
	v_pk_mul_f32 v[156:157], v[170:171], v[172:173]
	v_pk_fma_f32 v[104:105], v[104:105], v[108:109], v[132:133]
	v_pk_fma_f32 v[102:103], v[102:103], v[106:107], v[130:131]
	v_pk_mul_f32 v[104:105], v[156:157], v[104:105]
	v_pk_mul_f32 v[102:103], v[150:151], v[102:103]
	v_add_f32_e32 v186, 1.0, v186
	v_cvt_pk_bf16_f32 v102, v102, v103
	v_cvt_pk_bf16_f32 v103, v104, v105
	v_mov_b64_e32 v[104:105], s[36:37]
	v_add_f32_e32 v187, 1.0, v187
	v_add_f32_e32 v198, 1.0, v198
	v_add_f32_e32 v199, 1.0, v199
	v_mad_i64_i32 v[130:131], s[0:1], v0, s46, v[104:105]
	v_lshlrev_b64 v[132:133], 1, v[180:181]
	v_mov_b32_e32 v158, v1
	v_mov_b32_e32 v170, v1
	v_mov_b32_e32 v172, v1
	v_mov_b32_e32 v180, v1
	v_rcp_f32_e32 v186, v186
	v_rcp_f32_e32 v187, v187
	v_rcp_f32_e32 v198, v198
	v_rcp_f32_e32 v199, v199
	v_lshl_add_u64 v[130:131], v[130:131], 0, v[132:133]
	v_mov_b32_e32 v0, v1
	v_mov_b32_dpp v158, v98 row_ror:2 row_mask:0xf bank_mask:0xf
	v_mov_b32_e32 v159, v1
	v_mov_b32_dpp v170, v99 row_ror:2 row_mask:0xf bank_mask:0xf
	v_mov_b32_e32 v171, v1
	v_mov_b32_dpp v172, v100 row_ror:2 row_mask:0xf bank_mask:0xf
	v_mov_b32_e32 v173, v1
	v_mov_b32_dpp v180, v101 row_ror:2 row_mask:0xf bank_mask:0xf
	global_store_dwordx2 v[130:131], v[102:103], off
	v_mov_b32_dpp v0, v98 row_ror:1 row_mask:0xf bank_mask:0xf
	v_mov_b32_dpp v159, v99 row_ror:1 row_mask:0xf bank_mask:0xf
	v_mov_b32_dpp v171, v100 row_ror:1 row_mask:0xf bank_mask:0xf
	v_mov_b32_dpp v173, v101 row_ror:1 row_mask:0xf bank_mask:0xf
	v_cndmask_b32_e32 v102, v177, v158, vcc
	v_cndmask_b32_e32 v103, v179, v170, vcc
	v_cndmask_b32_e32 v130, v183, v172, vcc
	v_cndmask_b32_e32 v131, v201, v180, vcc
	v_cndmask_b32_e64 v134, v0, v176, s[42:43]
	v_cndmask_b32_e64 v135, v159, v178, s[42:43]
	v_cndmask_b32_e64 v136, v171, v182, s[42:43]
	v_cndmask_b32_e64 v137, v173, v200, s[42:43]
	v_pk_fma_f32 v[130:131], v[116:117], v[130:131], v[120:121]
	v_pk_fma_f32 v[102:103], v[114:115], v[102:103], v[118:119]
	v_mul_f32_e32 v126, 0xbfb8aa3b, v122
	v_mul_f32_e32 v127, 0xbfb8aa3b, v123
	v_pk_fma_f32 v[130:131], v[112:113], v[136:137], v[130:131]
	v_pk_fma_f32 v[102:103], v[110:111], v[134:135], v[102:103]
	v_exp_f32_e32 v126, v126
	v_exp_f32_e32 v127, v127
	v_pk_mul_f32 v[150:151], v[184:185], v[186:187]
	v_pk_mul_f32 v[156:157], v[188:189], v[198:199]
	v_pk_fma_f32 v[100:101], v[100:101], v[108:109], v[130:131]
	v_pk_fma_f32 v[98:99], v[98:99], v[106:107], v[102:103]
	v_pk_mul_f32 v[100:101], v[156:157], v[100:101]
	v_pk_mul_f32 v[98:99], v[150:151], v[98:99]
	v_add_f32_e32 v126, 1.0, v126
	v_cvt_pk_bf16_f32 v98, v98, v99
	v_cvt_pk_bf16_f32 v99, v100, v101
	v_mad_i64_i32 v[100:101], s[0:1], v174, s46, v[104:105]
	v_lshl_add_u64 v[100:101], v[100:101], 0, v[132:133]
	v_add_f32_e32 v127, 1.0, v127
	global_store_dwordx2 v[100:101], v[98:99], off
	v_mov_b32_e32 v98, v1
	v_mov_b32_e32 v99, v1
	v_mov_b32_e32 v100, v1
	v_mov_b32_e32 v101, v1
	v_rcp_f32_e32 v126, v126
	v_rcp_f32_e32 v127, v127
	v_mov_b32_e32 v102, v1
	v_mov_b32_dpp v98, v154 row_ror:2 row_mask:0xf bank_mask:0xf
	v_mov_b32_e32 v103, v1
	v_mov_b32_dpp v99, v155 row_ror:2 row_mask:0xf bank_mask:0xf
	v_mov_b32_e32 v130, v1
	v_mov_b32_dpp v100, v152 row_ror:2 row_mask:0xf bank_mask:0xf
	v_mov_b32_e32 v131, v1
	v_mov_b32_dpp v101, v153 row_ror:2 row_mask:0xf bank_mask:0xf
	v_mov_b32_dpp v102, v154 row_ror:1 row_mask:0xf bank_mask:0xf
	v_mov_b32_dpp v103, v155 row_ror:1 row_mask:0xf bank_mask:0xf
	v_mov_b32_dpp v130, v152 row_ror:1 row_mask:0xf bank_mask:0xf
	v_mov_b32_dpp v131, v153 row_ror:1 row_mask:0xf bank_mask:0xf
	v_cndmask_b32_e32 v98, v158, v98, vcc
	v_cndmask_b32_e32 v99, v170, v99, vcc
	v_cndmask_b32_e32 v100, v172, v100, vcc
	v_cndmask_b32_e32 v101, v180, v101, vcc
	v_cndmask_b32_e64 v102, v102, v0, s[42:43]
	v_cndmask_b32_e64 v103, v103, v159, s[42:43]
	v_cndmask_b32_e64 v130, v130, v171, s[42:43]
	v_cndmask_b32_e64 v131, v131, v173, s[42:43]
	v_pk_fma_f32 v[98:99], v[114:115], v[98:99], v[118:119]
	v_pk_fma_f32 v[100:101], v[116:117], v[100:101], v[120:121]
	v_pk_fma_f32 v[98:99], v[110:111], v[102:103], v[98:99]
	v_pk_fma_f32 v[100:101], v[112:113], v[130:131], v[100:101]
	v_pk_mul_f32 v[122:123], v[122:123], v[126:127]
	v_pk_mul_f32 v[124:125], v[124:125], v[128:129]
	v_pk_fma_f32 v[98:99], v[154:155], v[106:107], v[98:99]
	v_pk_fma_f32 v[100:101], v[152:153], v[108:109], v[100:101]
	v_pk_mul_f32 v[98:99], v[122:123], v[98:99]
	v_pk_mul_f32 v[100:101], v[124:125], v[100:101]
	v_cvt_pk_bf16_f32 v98, v98, v99
	s_nop 0
	v_cvt_pk_bf16_f32 v99, v100, v101
	v_mad_i64_i32 v[100:101], s[0:1], v175, s46, v[104:105]
	v_lshl_add_u64 v[100:101], v[100:101], 0, v[132:133]
	global_store_dwordx2 v[100:101], v[98:99], off
	s_add_i32 s0, s6, 2
	v_and_b32_e32 v129, 15, v226
	v_or_b32_e32 v106, s4, v129
	v_ashrrev_i32_e32 v107, 31, v106
	v_lshl_add_u64 v[104:105], v[106:107], 3, s[38:39]
	global_load_dwordx2 v[108:109], v[104:105], off offset:1024
	global_load_dwordx2 v[102:103], v[104:105], off offset:1152
	global_load_dwordx2 v[100:101], v[104:105], off offset:1280
	s_nop 0
	global_load_dwordx2 v[104:105], v[104:105], off offset:1408
	v_ashrrev_i32_e32 v0, 1, v226
	v_and_b32_e32 v0, -8, v0
	v_add_u32_e32 v98, s21, v0
	s_mul_hi_i32 s1, s0, 0xb000
	s_mul_i32 s0, s0, 0xb000
	s_add_u32 s0, s18, s0
	s_addc_u32 s1, s19, s1
	s_add_u32 s78, s0, s80
	s_addc_u32 s79, s1, s81
	s_waitcnt vmcnt(3)
	v_ffbh_u32_e32 v0, v109
	v_min_u32_e32 v0, 32, v0
	v_lshlrev_b64 v[108:109], v0, v[108:109]
	v_min_u32_e32 v99, 1, v108
	v_or_b32_e32 v99, v109, v99
	v_cvt_f32_u32_e32 v99, v99
	v_sub_u32_e32 v0, 32, v0
	v_ldexp_f32 v0, v99, v0
	v_mul_f32_e32 v0, 0x33800000, v0
	v_fmamk_f32 v0, v0, 0x3a800000, v210
	v_cmp_gt_f32_e32 vcc, s35, v0
	v_mul_f32_e32 v99, 0x4b800000, v0
	s_nop 0
	v_cndmask_b32_e32 v0, v0, v99, vcc
	v_rsq_f32_e32 v0, v0
	s_nop 0
	v_mul_f32_e32 v99, 0x45800000, v0
	v_cndmask_b32_e32 v0, v0, v99, vcc
	v_ashrrev_i32_e32 v99, 31, v98
	v_pk_mul_f32 v[118:119], v[96:97], v[0:1] op_sel_hi:[1,0]
	v_pk_mul_f32 v[116:117], v[94:95], v[0:1] op_sel_hi:[1,0]
	v_pk_mul_f32 v[112:113], v[92:93], v[0:1] op_sel_hi:[1,0]
	v_pk_mul_f32 v[114:115], v[90:91], v[0:1] op_sel_hi:[1,0]
	v_lshl_add_u64 v[90:91], v[98:99], 1, s[78:79]
	v_cmp_gt_u32_e32 vcc, 2, v129
	s_and_saveexec_b64 s[0:1], vcc
	s_cbranch_execz .LBB0_117
	v_mul_u32_u24_e32 v0, 0x1600, v129
	v_lshlrev_b32_e32 v0, 1, v0
	v_cvt_pk_bf16_f32 v92, v116, v117
	v_cvt_pk_bf16_f32 v93, v118, v119
	v_lshl_add_u64 v[96:97], v[90:91], 0, v[0:1]
	v_cvt_pk_bf16_f32 v94, v114, v115
	v_cvt_pk_bf16_f32 v95, v112, v113
	global_store_dwordx2 v[96:97], v[92:93], off
	global_store_dwordx2 v[96:97], v[94:95], off offset:256

.LBB0_121:
	s_or_b64 exec, exec, s[0:1]
	v_cmp_eq_u32_e64 s[42:43], 0, v129
	v_cndmask_b32_e32 v115, v173, v194, vcc
	v_cndmask_b32_e32 v114, v172, v190, vcc
	v_cndmask_b32_e64 v113, v195, v175, s[42:43]
	v_cndmask_b32_e64 v112, v191, v174, s[42:43]
	s_waitcnt vmcnt(4)
	v_pk_fma_f32 v[114:115], v[90:91], v[114:115], v[102:103]
	v_cndmask_b32_e32 v119, v159, v183, vcc
	v_cndmask_b32_e32 v118, v158, v178, vcc
	v_pk_fma_f32 v[112:113], v[94:95], v[112:113], v[114:115]
	v_cndmask_b32_e64 v117, v185, v171, s[42:43]
	v_cndmask_b32_e64 v116, v179, v170, s[42:43]
	v_pk_fma_f32 v[118:119], v[92:93], v[118:119], v[104:105]
	v_pk_fma_f32 v[112:113], v[132:133], v[98:99], v[112:113]
	v_pk_fma_f32 v[116:117], v[96:97], v[116:117], v[118:119]
	v_cndmask_b32_e32 v133, v194, v187, vcc
	v_cndmask_b32_e32 v132, v190, v181, vcc
	v_pk_fma_f32 v[116:117], v[130:131], v[100:101], v[116:117]
	v_cndmask_b32_e64 v131, v189, v195, s[42:43]
	v_cndmask_b32_e64 v130, v184, v191, s[42:43]
	v_pk_fma_f32 v[132:133], v[90:91], v[132:133], v[102:103]
	v_cndmask_b32_e32 v159, v183, v176, vcc
	v_pk_fma_f32 v[130:131], v[94:95], v[130:131], v[132:133]
	v_cndmask_b32_e32 v158, v178, v0, vcc
	v_pk_fma_f32 v[130:131], v[156:157], v[98:99], v[130:131]
	v_cndmask_b32_e64 v157, v177, v185, s[42:43]
	v_cndmask_b32_e64 v156, v107, v179, s[42:43]
	v_pk_fma_f32 v[158:159], v[92:93], v[158:159], v[104:105]
	v_cndmask_b32_e32 v171, v187, v196, vcc
	v_cndmask_b32_e32 v170, v181, v192, vcc
	v_pk_fma_f32 v[156:157], v[96:97], v[156:157], v[158:159]
	v_cndmask_b32_e64 v159, v197, v189, s[42:43]
	v_cndmask_b32_e64 v158, v193, v184, s[42:43]
	v_pk_fma_f32 v[90:91], v[90:91], v[170:171], v[102:103]
	v_cndmask_b32_e32 v103, v176, v186, vcc
	v_pk_fma_f32 v[90:91], v[94:95], v[158:159], v[90:91]
	v_cndmask_b32_e32 v102, v0, v180, vcc
	v_mul_f32_e32 v114, 0xbfb8aa3b, v112
	v_mul_f32_e32 v115, 0xbfb8aa3b, v113
	v_mul_f32_e32 v118, 0xbfb8aa3b, v116
	v_mul_f32_e32 v119, 0xbfb8aa3b, v117
	v_pk_fma_f32 v[90:91], v[122:123], v[98:99], v[90:91]
	v_cndmask_b32_e64 v99, v188, v177, s[42:43]
	v_cndmask_b32_e64 v98, v182, v107, s[42:43]
	v_pk_fma_f32 v[92:93], v[92:93], v[102:103], v[104:105]
	v_exp_f32_e32 v114, v114
	v_exp_f32_e32 v115, v115
	v_exp_f32_e32 v118, v118
	v_exp_f32_e32 v119, v119
	v_pk_fma_f32 v[92:93], v[96:97], v[98:99], v[92:93]
	v_mov_b32_e32 v125, v124
	v_pk_fma_f32 v[92:93], v[120:121], v[100:101], v[92:93]
	v_mov_b32_e32 v129, v128
	v_mul_f32_e32 v0, 0xbfb8aa3b, v92
	v_exp_f32_e32 v0, v0
	v_mul_f32_e32 v96, 0xbfb8aa3b, v93
	v_mov_b32_e32 v98, v124
	v_mov_b32_e32 v99, v124
	v_add_f32_e32 v114, 1.0, v114
	v_add_f32_e32 v115, 1.0, v115
	v_add_f32_e32 v118, 1.0, v118
	v_add_f32_e32 v119, 1.0, v119
	v_exp_f32_e32 v97, v96
	v_pk_mul_f32 v[72:73], v[72:73], v[98:99]
	v_pk_mul_f32 v[70:71], v[70:71], v[124:125]
	v_pk_mul_f32 v[66:67], v[66:67], v[128:129]
	v_mov_b32_e32 v123, v1
	v_mov_b32_e32 v125, v1
	v_mov_b32_e32 v129, v1
	v_mov_b32_e32 v159, v1
	v_rcp_f32_e32 v114, v114
	v_rcp_f32_e32 v115, v115
	v_rcp_f32_e32 v118, v118
	v_rcp_f32_e32 v119, v119
	v_mov_b32_e32 v98, v128
	v_mov_b32_e32 v99, v128
	v_mov_b32_e32 v122, v1
	v_mov_b32_dpp v123, v70 row_ror:2 row_mask:0xf bank_mask:0xf
	v_mov_b32_e32 v124, v1
	v_mov_b32_dpp v125, v71 row_ror:2 row_mask:0xf bank_mask:0xf
	v_mov_b32_e32 v128, v1
	v_mov_b32_dpp v129, v72 row_ror:2 row_mask:0xf bank_mask:0xf
	v_mov_b32_e32 v158, v1
	v_mov_b32_dpp v159, v73 row_ror:2 row_mask:0xf bank_mask:0xf
	v_pk_fma_f32 v[134:135], v[134:135], v[100:101], v[156:157]
	v_pk_mul_f32 v[68:69], v[68:69], v[98:99]
	v_mov_b32_dpp v122, v70 row_ror:1 row_mask:0xf bank_mask:0xf
	v_mov_b32_dpp v124, v71 row_ror:1 row_mask:0xf bank_mask:0xf
	v_mov_b32_dpp v128, v72 row_ror:1 row_mask:0xf bank_mask:0xf
	v_mov_b32_dpp v158, v73 row_ror:1 row_mask:0xf bank_mask:0xf
	v_cndmask_b32_e32 v98, v152, v123, vcc
	v_cndmask_b32_e32 v99, v153, v125, vcc
	v_cndmask_b32_e32 v100, v154, v129, vcc
	v_cndmask_b32_e32 v101, v155, v159, vcc
	v_mul_f32_e32 v132, 0xbfb8aa3b, v130
	v_mul_f32_e32 v133, 0xbfb8aa3b, v131
	v_mul_f32_e32 v156, 0xbfb8aa3b, v134
	v_mul_f32_e32 v157, 0xbfb8aa3b, v135
	v_add_f32_e32 v0, 1.0, v0
	v_cndmask_b32_e64 v102, v122, v136, s[42:43]
	v_cndmask_b32_e64 v103, v124, v137, s[42:43]
	v_cndmask_b32_e64 v104, v128, v150, s[42:43]
	v_cndmask_b32_e64 v105, v158, v151, s[42:43]
	s_waitcnt vmcnt(1)
	v_pk_fma_f32 v[100:101], v[84:85], v[100:101], v[88:89]
	v_pk_fma_f32 v[98:99], v[82:83], v[98:99], v[86:87]
	v_exp_f32_e32 v132, v132
	v_exp_f32_e32 v133, v133
	v_exp_f32_e32 v156, v156
	v_exp_f32_e32 v157, v157
	v_rcp_f32_e32 v96, v0
	v_add_f32_e32 v0, 1.0, v97
	v_pk_fma_f32 v[100:101], v[80:81], v[104:105], v[100:101]
	v_pk_fma_f32 v[98:99], v[78:79], v[102:103], v[98:99]
	v_rcp_f32_e32 v97, v0
	v_add_u32_e32 v0, 0x90, v106
	v_add_u32_e32 v120, 0xa0, v106
	v_add_u32_e32 v121, 0xb0, v106
	v_pk_mul_f32 v[106:107], v[112:113], v[114:115]
	v_pk_mul_f32 v[112:113], v[116:117], v[118:119]
	v_pk_fma_f32 v[72:73], v[72:73], v[76:77], v[100:101]
	v_pk_fma_f32 v[70:71], v[70:71], v[74:75], v[98:99]
	v_pk_mul_f32 v[72:73], v[112:113], v[72:73]
	v_pk_mul_f32 v[70:71], v[106:107], v[70:71]
	v_add_f32_e32 v132, 1.0, v132
	v_cvt_pk_bf16_f32 v70, v70, v71
	v_cvt_pk_bf16_f32 v71, v72, v73
	v_mov_b64_e32 v[72:73], s[36:37]
	v_add_f32_e32 v133, 1.0, v133
	v_add_f32_e32 v156, 1.0, v156
	v_add_f32_e32 v157, 1.0, v157
	v_mad_i64_i32 v[98:99], s[0:1], v0, s46, v[72:73]
	v_lshlrev_b64 v[100:101], 1, v[126:127]
	v_mov_b32_e32 v114, v1
	v_mov_b32_e32 v116, v1
	v_mov_b32_e32 v118, v1
	v_mov_b32_e32 v126, v1
	v_rcp_f32_e32 v132, v132
	v_rcp_f32_e32 v133, v133
	v_rcp_f32_e32 v156, v156
	v_rcp_f32_e32 v157, v157
	v_lshl_add_u64 v[98:99], v[98:99], 0, v[100:101]
	v_mov_b32_e32 v0, v1
	v_mov_b32_dpp v114, v66 row_ror:2 row_mask:0xf bank_mask:0xf
	v_mov_b32_e32 v115, v1
	v_mov_b32_dpp v116, v67 row_ror:2 row_mask:0xf bank_mask:0xf
	v_mov_b32_e32 v117, v1
	v_mov_b32_dpp v118, v68 row_ror:2 row_mask:0xf bank_mask:0xf
	v_mov_b32_e32 v119, v1
	v_mov_b32_dpp v126, v69 row_ror:2 row_mask:0xf bank_mask:0xf
	global_store_dwordx2 v[98:99], v[70:71], off
	v_mov_b32_dpp v0, v66 row_ror:1 row_mask:0xf bank_mask:0xf
	v_mov_b32_dpp v115, v67 row_ror:1 row_mask:0xf bank_mask:0xf
	v_mov_b32_dpp v117, v68 row_ror:1 row_mask:0xf bank_mask:0xf
	v_mov_b32_dpp v119, v69 row_ror:1 row_mask:0xf bank_mask:0xf
	v_cndmask_b32_e32 v70, v123, v114, vcc
	v_cndmask_b32_e32 v71, v125, v116, vcc
	v_cndmask_b32_e32 v98, v129, v118, vcc
	v_cndmask_b32_e32 v99, v159, v126, vcc
	v_cndmask_b32_e64 v102, v0, v122, s[42:43]
	v_cndmask_b32_e64 v103, v115, v124, s[42:43]
	v_cndmask_b32_e64 v104, v117, v128, s[42:43]
	v_cndmask_b32_e64 v105, v119, v158, s[42:43]
	v_pk_fma_f32 v[98:99], v[84:85], v[98:99], v[88:89]
	v_pk_fma_f32 v[70:71], v[82:83], v[70:71], v[86:87]
	v_mul_f32_e32 v94, 0xbfb8aa3b, v90
	v_mul_f32_e32 v95, 0xbfb8aa3b, v91
	v_pk_fma_f32 v[98:99], v[80:81], v[104:105], v[98:99]
	v_pk_fma_f32 v[70:71], v[78:79], v[102:103], v[70:71]
	v_exp_f32_e32 v94, v94
	v_exp_f32_e32 v95, v95
	v_pk_mul_f32 v[106:107], v[130:131], v[132:133]
	v_pk_mul_f32 v[112:113], v[134:135], v[156:157]
	v_pk_fma_f32 v[68:69], v[68:69], v[76:77], v[98:99]
	v_pk_fma_f32 v[66:67], v[66:67], v[74:75], v[70:71]
	v_pk_mul_f32 v[68:69], v[112:113], v[68:69]
	v_pk_mul_f32 v[66:67], v[106:107], v[66:67]
	v_add_f32_e32 v94, 1.0, v94
	v_cvt_pk_bf16_f32 v66, v66, v67
	v_cvt_pk_bf16_f32 v67, v68, v69
	v_mad_i64_i32 v[68:69], s[0:1], v120, s46, v[72:73]
	v_lshl_add_u64 v[68:69], v[68:69], 0, v[100:101]
	v_add_f32_e32 v95, 1.0, v95
	global_store_dwordx2 v[68:69], v[66:67], off
	v_mov_b32_e32 v66, v1
	v_mov_b32_e32 v67, v1
	v_mov_b32_e32 v68, v1
	v_mov_b32_e32 v69, v1
	v_rcp_f32_e32 v94, v94
	v_rcp_f32_e32 v95, v95
	v_mov_b32_e32 v70, v1
	v_mov_b32_dpp v66, v110 row_ror:2 row_mask:0xf bank_mask:0xf
	v_mov_b32_e32 v71, v1
	v_mov_b32_dpp v67, v111 row_ror:2 row_mask:0xf bank_mask:0xf
	v_mov_b32_e32 v98, v1
	v_mov_b32_dpp v68, v108 row_ror:2 row_mask:0xf bank_mask:0xf
	v_mov_b32_e32 v99, v1
	v_mov_b32_dpp v69, v109 row_ror:2 row_mask:0xf bank_mask:0xf
	v_mov_b32_dpp v70, v110 row_ror:1 row_mask:0xf bank_mask:0xf
	v_mov_b32_dpp v71, v111 row_ror:1 row_mask:0xf bank_mask:0xf
	v_mov_b32_dpp v98, v108 row_ror:1 row_mask:0xf bank_mask:0xf
	v_mov_b32_dpp v99, v109 row_ror:1 row_mask:0xf bank_mask:0xf
	v_cndmask_b32_e32 v66, v114, v66, vcc
	v_cndmask_b32_e32 v67, v116, v67, vcc
	v_cndmask_b32_e32 v68, v118, v68, vcc
	v_cndmask_b32_e32 v69, v126, v69, vcc
	v_cndmask_b32_e64 v70, v70, v0, s[42:43]
	v_cndmask_b32_e64 v71, v71, v115, s[42:43]
	v_cndmask_b32_e64 v98, v98, v117, s[42:43]
	v_cndmask_b32_e64 v99, v99, v119, s[42:43]
	v_pk_fma_f32 v[66:67], v[82:83], v[66:67], v[86:87]
	v_pk_fma_f32 v[68:69], v[84:85], v[68:69], v[88:89]
	v_pk_fma_f32 v[66:67], v[78:79], v[70:71], v[66:67]
	v_pk_fma_f32 v[68:69], v[80:81], v[98:99], v[68:69]
	v_pk_mul_f32 v[90:91], v[90:91], v[94:95]
	v_pk_mul_f32 v[92:93], v[92:93], v[96:97]
	v_pk_fma_f32 v[66:67], v[110:111], v[74:75], v[66:67]
	v_pk_fma_f32 v[68:69], v[108:109], v[76:77], v[68:69]
	v_pk_mul_f32 v[66:67], v[90:91], v[66:67]
	v_pk_mul_f32 v[68:69], v[92:93], v[68:69]
	v_cvt_pk_bf16_f32 v66, v66, v67
	s_nop 0
	v_cvt_pk_bf16_f32 v67, v68, v69
	v_mad_i64_i32 v[68:69], s[0:1], v121, s46, v[72:73]
	v_lshl_add_u64 v[68:69], v[68:69], 0, v[100:101]
	global_store_dwordx2 v[68:69], v[66:67], off
	s_nop 0
	v_and_b32_e32 v97, 15, v226
	v_or_b32_e32 v74, s4, v97
	v_ashrrev_i32_e32 v75, 31, v74
	v_lshl_add_u64 v[72:73], v[74:75], 3, s[38:39]
	global_load_dwordx2 v[76:77], v[72:73], off
	global_load_dwordx2 v[70:71], v[72:73], off offset:128
	global_load_dwordx2 v[68:69], v[72:73], off offset:256
	s_nop 0
	global_load_dwordx2 v[72:73], v[72:73], off offset:384
	v_ashrrev_i32_e32 v0, 1, v226
	v_and_b32_e32 v0, -8, v0
	v_add_u32_e32 v66, s21, v0
	s_waitcnt vmcnt(3)
	v_ffbh_u32_e32 v0, v77
	v_min_u32_e32 v0, 32, v0
	v_lshlrev_b64 v[76:77], v0, v[76:77]
	v_min_u32_e32 v67, 1, v76
	v_or_b32_e32 v67, v77, v67
	v_cvt_f32_u32_e32 v67, v67
	v_sub_u32_e32 v0, 32, v0
	v_ldexp_f32 v0, v67, v0
	v_mul_f32_e32 v0, 0x33800000, v0
	v_fmamk_f32 v0, v0, 0x3a800000, v210
	v_cmp_gt_f32_e32 vcc, s35, v0
	v_mul_f32_e32 v67, 0x4b800000, v0
	s_nop 0
	v_cndmask_b32_e32 v0, v0, v67, vcc
	v_rsq_f32_e32 v0, v0
	s_nop 0
	v_mul_f32_e32 v67, 0x45800000, v0
	v_cndmask_b32_e32 v0, v0, v67, vcc
	v_ashrrev_i32_e32 v67, 31, v66
	v_pk_mul_f32 v[92:93], v[64:65], v[0:1] op_sel_hi:[1,0]
	v_pk_mul_f32 v[90:91], v[62:63], v[0:1] op_sel_hi:[1,0]
	v_pk_mul_f32 v[86:87], v[60:61], v[0:1] op_sel_hi:[1,0]
	v_pk_mul_f32 v[88:89], v[58:59], v[0:1] op_sel_hi:[1,0]
	v_lshl_add_u64 v[58:59], v[66:67], 1, s[76:77]
	v_cmp_gt_u32_e32 vcc, 2, v97
	s_and_saveexec_b64 s[0:1], vcc
	s_cbranch_execz .LBB0_123
	v_mul_u32_u24_e32 v0, 0x1600, v97
	v_lshlrev_b32_e32 v0, 1, v0
	v_cvt_pk_bf16_f32 v60, v90, v91
	v_cvt_pk_bf16_f32 v61, v92, v93
	v_lshl_add_u64 v[64:65], v[58:59], 0, v[0:1]
	v_cvt_pk_bf16_f32 v62, v88, v89
	v_cvt_pk_bf16_f32 v63, v86, v87
	global_store_dwordx2 v[64:65], v[60:61], off offset:8
	global_store_dwordx2 v[64:65], v[62:63], off offset:264

.LBB0_127:
	s_or_b64 exec, exec, s[0:1]
	v_cmp_eq_u32_e64 s[42:43], 0, v97
	v_cndmask_b32_e32 v89, v119, v152, vcc
	v_cndmask_b32_e32 v88, v118, v136, vcc
	v_cndmask_b32_e64 v87, v153, v121, s[42:43]
	v_cndmask_b32_e64 v86, v137, v120, s[42:43]
	s_waitcnt vmcnt(4)
	v_pk_fma_f32 v[88:89], v[58:59], v[88:89], v[70:71]
	v_cndmask_b32_e32 v93, v115, v129, vcc
	v_cndmask_b32_e32 v92, v114, v124, vcc
	v_pk_fma_f32 v[86:87], v[62:63], v[86:87], v[88:89]
	v_cndmask_b32_e64 v91, v131, v117, s[42:43]
	v_cndmask_b32_e64 v90, v125, v116, s[42:43]
	v_pk_fma_f32 v[92:93], v[60:61], v[92:93], v[72:73]
	v_pk_fma_f32 v[86:87], v[100:101], v[66:67], v[86:87]
	v_pk_fma_f32 v[90:91], v[64:65], v[90:91], v[92:93]
	v_cndmask_b32_e32 v101, v152, v133, vcc
	v_cndmask_b32_e32 v100, v136, v127, vcc
	v_pk_fma_f32 v[90:91], v[98:99], v[68:69], v[90:91]
	v_cndmask_b32_e64 v99, v135, v153, s[42:43]
	v_cndmask_b32_e64 v98, v130, v137, s[42:43]
	v_pk_fma_f32 v[100:101], v[58:59], v[100:101], v[70:71]
	v_cndmask_b32_e32 v115, v129, v122, vcc
	v_pk_fma_f32 v[98:99], v[62:63], v[98:99], v[100:101]
	v_cndmask_b32_e32 v114, v124, v0, vcc
	v_pk_fma_f32 v[98:99], v[112:113], v[66:67], v[98:99]
	v_cndmask_b32_e64 v113, v123, v131, s[42:43]
	v_cndmask_b32_e64 v112, v75, v125, s[42:43]
	v_pk_fma_f32 v[114:115], v[60:61], v[114:115], v[72:73]
	v_cndmask_b32_e32 v117, v133, v154, vcc
	v_cndmask_b32_e32 v116, v127, v150, vcc
	v_pk_fma_f32 v[112:113], v[64:65], v[112:113], v[114:115]
	v_cndmask_b32_e64 v115, v155, v135, s[42:43]
	v_cndmask_b32_e64 v114, v151, v130, s[42:43]
	v_pk_fma_f32 v[58:59], v[58:59], v[116:117], v[70:71]
	v_cndmask_b32_e32 v71, v122, v132, vcc
	v_pk_fma_f32 v[58:59], v[62:63], v[114:115], v[58:59]
	v_cndmask_b32_e32 v70, v0, v126, vcc
	v_mul_f32_e32 v88, 0xbfb8aa3b, v86
	v_mul_f32_e32 v89, 0xbfb8aa3b, v87
	v_mul_f32_e32 v92, 0xbfb8aa3b, v90
	v_mul_f32_e32 v93, 0xbfb8aa3b, v91
	v_pk_fma_f32 v[58:59], v[82:83], v[66:67], v[58:59]
	v_cndmask_b32_e64 v67, v134, v123, s[42:43]
	v_cndmask_b32_e64 v66, v128, v75, s[42:43]
	v_pk_fma_f32 v[60:61], v[60:61], v[70:71], v[72:73]
	v_exp_f32_e32 v88, v88
	v_exp_f32_e32 v89, v89
	v_exp_f32_e32 v92, v92
	v_exp_f32_e32 v93, v93
	v_pk_fma_f32 v[60:61], v[64:65], v[66:67], v[60:61]
	v_mov_b32_e32 v85, v84
	v_pk_fma_f32 v[60:61], v[80:81], v[68:69], v[60:61]
	v_mov_b32_e32 v97, v96
	v_mul_f32_e32 v0, 0xbfb8aa3b, v60
	v_exp_f32_e32 v0, v0
	v_mul_f32_e32 v64, 0xbfb8aa3b, v61
	v_mov_b32_e32 v66, v84
	v_mov_b32_e32 v67, v84
	v_add_f32_e32 v88, 1.0, v88
	v_add_f32_e32 v89, 1.0, v89
	v_add_f32_e32 v92, 1.0, v92
	v_add_f32_e32 v93, 1.0, v93
	v_exp_f32_e32 v65, v64
	v_pk_mul_f32 v[40:41], v[40:41], v[66:67]
	v_pk_mul_f32 v[38:39], v[38:39], v[84:85]
	v_pk_mul_f32 v[34:35], v[34:35], v[96:97]
	v_mov_b32_e32 v85, v1
	v_mov_b32_e32 v97, v1
	v_mov_b32_e32 v115, v1
	v_mov_b32_e32 v117, v1
	v_rcp_f32_e32 v88, v88
	v_rcp_f32_e32 v89, v89
	v_rcp_f32_e32 v92, v92
	v_rcp_f32_e32 v93, v93
	v_mov_b32_e32 v66, v96
	v_mov_b32_e32 v67, v96
	v_mov_b32_e32 v84, v1
	v_mov_b32_dpp v85, v38 row_ror:2 row_mask:0xf bank_mask:0xf
	v_mov_b32_e32 v96, v1
	v_mov_b32_dpp v97, v39 row_ror:2 row_mask:0xf bank_mask:0xf
	v_mov_b32_e32 v114, v1
	v_mov_b32_dpp v115, v40 row_ror:2 row_mask:0xf bank_mask:0xf
	v_mov_b32_e32 v116, v1
	v_mov_b32_dpp v117, v41 row_ror:2 row_mask:0xf bank_mask:0xf
	v_pk_fma_f32 v[102:103], v[102:103], v[68:69], v[112:113]
	v_pk_mul_f32 v[36:37], v[36:37], v[66:67]
	v_mov_b32_dpp v84, v38 row_ror:1 row_mask:0xf bank_mask:0xf
	v_mov_b32_dpp v96, v39 row_ror:1 row_mask:0xf bank_mask:0xf
	v_mov_b32_dpp v114, v40 row_ror:1 row_mask:0xf bank_mask:0xf
	v_mov_b32_dpp v116, v41 row_ror:1 row_mask:0xf bank_mask:0xf
	v_cndmask_b32_e32 v66, v108, v85, vcc
	v_cndmask_b32_e32 v67, v109, v97, vcc
	v_cndmask_b32_e32 v68, v110, v115, vcc
	v_cndmask_b32_e32 v69, v111, v117, vcc
	v_mul_f32_e32 v100, 0xbfb8aa3b, v98
	v_mul_f32_e32 v101, 0xbfb8aa3b, v99
	v_mul_f32_e32 v112, 0xbfb8aa3b, v102
	v_mul_f32_e32 v113, 0xbfb8aa3b, v103
	v_add_f32_e32 v0, 1.0, v0
	v_cndmask_b32_e64 v70, v84, v104, s[42:43]
	v_cndmask_b32_e64 v71, v96, v105, s[42:43]
	v_cndmask_b32_e64 v72, v114, v106, s[42:43]
	v_cndmask_b32_e64 v73, v116, v107, s[42:43]
	s_waitcnt vmcnt(1)
	v_pk_fma_f32 v[68:69], v[52:53], v[68:69], v[56:57]
	v_pk_fma_f32 v[66:67], v[50:51], v[66:67], v[54:55]
	v_exp_f32_e32 v100, v100
	v_exp_f32_e32 v101, v101
	v_exp_f32_e32 v112, v112
	v_exp_f32_e32 v113, v113
	v_rcp_f32_e32 v64, v0
	v_add_f32_e32 v0, 1.0, v65
	v_pk_fma_f32 v[68:69], v[48:49], v[72:73], v[68:69]
	v_pk_fma_f32 v[66:67], v[46:47], v[70:71], v[66:67]
	v_rcp_f32_e32 v65, v0
	v_or_b32_e32 v0, 16, v74
	v_or_b32_e32 v82, 32, v74
	v_or_b32_e32 v83, 48, v74
	v_pk_mul_f32 v[74:75], v[86:87], v[88:89]
	v_pk_mul_f32 v[80:81], v[90:91], v[92:93]
	v_pk_fma_f32 v[40:41], v[40:41], v[44:45], v[68:69]
	v_pk_fma_f32 v[38:39], v[38:39], v[42:43], v[66:67]
	v_pk_mul_f32 v[40:41], v[80:81], v[40:41]
	v_pk_mul_f32 v[38:39], v[74:75], v[38:39]
	v_add_f32_e32 v100, 1.0, v100
	v_cvt_pk_bf16_f32 v38, v38, v39
	v_cvt_pk_bf16_f32 v39, v40, v41
	v_mov_b64_e32 v[40:41], s[36:37]
	v_add_f32_e32 v101, 1.0, v101
	v_add_f32_e32 v112, 1.0, v112
	v_add_f32_e32 v113, 1.0, v113
	v_mad_i64_i32 v[66:67], s[0:1], v0, s46, v[40:41]
	v_lshlrev_b64 v[68:69], 1, v[94:95]
	v_mov_b32_e32 v86, v1
	v_mov_b32_e32 v88, v1
	v_mov_b32_e32 v90, v1
	v_mov_b32_e32 v92, v1
	v_rcp_f32_e32 v100, v100
	v_rcp_f32_e32 v101, v101
	v_rcp_f32_e32 v112, v112
	v_rcp_f32_e32 v113, v113
	v_lshl_add_u64 v[66:67], v[66:67], 0, v[68:69]
	v_mov_b32_e32 v0, v1
	v_mov_b32_dpp v86, v34 row_ror:2 row_mask:0xf bank_mask:0xf
	v_mov_b32_e32 v87, v1
	v_mov_b32_dpp v88, v35 row_ror:2 row_mask:0xf bank_mask:0xf
	v_mov_b32_e32 v89, v1
	v_mov_b32_dpp v90, v36 row_ror:2 row_mask:0xf bank_mask:0xf
	v_mov_b32_e32 v91, v1
	v_mov_b32_dpp v92, v37 row_ror:2 row_mask:0xf bank_mask:0xf
	global_store_dwordx2 v[66:67], v[38:39], off
	v_mov_b32_dpp v0, v34 row_ror:1 row_mask:0xf bank_mask:0xf
	v_mov_b32_dpp v87, v35 row_ror:1 row_mask:0xf bank_mask:0xf
	v_mov_b32_dpp v89, v36 row_ror:1 row_mask:0xf bank_mask:0xf
	v_mov_b32_dpp v91, v37 row_ror:1 row_mask:0xf bank_mask:0xf
	v_cndmask_b32_e32 v38, v85, v86, vcc
	v_cndmask_b32_e32 v39, v97, v88, vcc
	v_cndmask_b32_e32 v66, v115, v90, vcc
	v_cndmask_b32_e32 v67, v117, v92, vcc
	v_cndmask_b32_e64 v70, v0, v84, s[42:43]
	v_cndmask_b32_e64 v71, v87, v96, s[42:43]
	v_cndmask_b32_e64 v72, v89, v114, s[42:43]
	v_cndmask_b32_e64 v73, v91, v116, s[42:43]
	v_pk_fma_f32 v[66:67], v[52:53], v[66:67], v[56:57]
	v_pk_fma_f32 v[38:39], v[50:51], v[38:39], v[54:55]
	v_mul_f32_e32 v62, 0xbfb8aa3b, v58
	v_mul_f32_e32 v63, 0xbfb8aa3b, v59
	v_pk_fma_f32 v[66:67], v[48:49], v[72:73], v[66:67]
	v_pk_fma_f32 v[38:39], v[46:47], v[70:71], v[38:39]
	v_exp_f32_e32 v62, v62
	v_exp_f32_e32 v63, v63
	v_pk_mul_f32 v[74:75], v[98:99], v[100:101]
	v_pk_mul_f32 v[80:81], v[102:103], v[112:113]
	v_pk_fma_f32 v[36:37], v[36:37], v[44:45], v[66:67]
	v_pk_fma_f32 v[34:35], v[34:35], v[42:43], v[38:39]
	v_pk_mul_f32 v[36:37], v[80:81], v[36:37]
	v_pk_mul_f32 v[34:35], v[74:75], v[34:35]
	v_add_f32_e32 v62, 1.0, v62
	v_cvt_pk_bf16_f32 v34, v34, v35
	v_cvt_pk_bf16_f32 v35, v36, v37
	v_mad_i64_i32 v[36:37], s[0:1], v82, s46, v[40:41]
	v_lshl_add_u64 v[36:37], v[36:37], 0, v[68:69]
	v_add_f32_e32 v63, 1.0, v63
	global_store_dwordx2 v[36:37], v[34:35], off
	v_mov_b32_e32 v34, v1
	v_mov_b32_e32 v35, v1
	v_mov_b32_e32 v36, v1
	v_mov_b32_e32 v37, v1
	v_rcp_f32_e32 v62, v62
	v_rcp_f32_e32 v63, v63
	v_mov_b32_e32 v38, v1
	v_mov_b32_dpp v34, v78 row_ror:2 row_mask:0xf bank_mask:0xf
	v_mov_b32_e32 v39, v1
	v_mov_b32_dpp v35, v79 row_ror:2 row_mask:0xf bank_mask:0xf
	v_mov_b32_e32 v66, v1
	v_mov_b32_dpp v36, v76 row_ror:2 row_mask:0xf bank_mask:0xf
	v_mov_b32_e32 v67, v1
	v_mov_b32_dpp v37, v77 row_ror:2 row_mask:0xf bank_mask:0xf
	v_mov_b32_dpp v38, v78 row_ror:1 row_mask:0xf bank_mask:0xf
	v_mov_b32_dpp v39, v79 row_ror:1 row_mask:0xf bank_mask:0xf
	v_mov_b32_dpp v66, v76 row_ror:1 row_mask:0xf bank_mask:0xf
	v_mov_b32_dpp v67, v77 row_ror:1 row_mask:0xf bank_mask:0xf
	v_cndmask_b32_e32 v34, v86, v34, vcc
	v_cndmask_b32_e32 v35, v88, v35, vcc
	v_cndmask_b32_e32 v36, v90, v36, vcc
	v_cndmask_b32_e32 v37, v92, v37, vcc
	v_cndmask_b32_e64 v38, v38, v0, s[42:43]
	v_cndmask_b32_e64 v39, v39, v87, s[42:43]
	v_cndmask_b32_e64 v66, v66, v89, s[42:43]
	v_cndmask_b32_e64 v67, v67, v91, s[42:43]
	v_pk_fma_f32 v[34:35], v[50:51], v[34:35], v[54:55]
	v_pk_fma_f32 v[36:37], v[52:53], v[36:37], v[56:57]
	v_pk_fma_f32 v[34:35], v[46:47], v[38:39], v[34:35]
	v_pk_fma_f32 v[36:37], v[48:49], v[66:67], v[36:37]
	v_pk_mul_f32 v[58:59], v[58:59], v[62:63]
	v_pk_mul_f32 v[60:61], v[60:61], v[64:65]
	v_pk_fma_f32 v[34:35], v[78:79], v[42:43], v[34:35]
	v_pk_fma_f32 v[36:37], v[76:77], v[44:45], v[36:37]
	v_pk_mul_f32 v[34:35], v[58:59], v[34:35]
	v_pk_mul_f32 v[36:37], v[60:61], v[36:37]
	v_cvt_pk_bf16_f32 v34, v34, v35
	s_nop 0
	v_cvt_pk_bf16_f32 v35, v36, v37
	v_mad_i64_i32 v[36:37], s[0:1], v83, s46, v[40:41]
	v_lshl_add_u64 v[36:37], v[36:37], 0, v[68:69]
	global_store_dwordx2 v[36:37], v[34:35], off
	s_nop 0
	v_and_b32_e32 v108, 15, v226
	v_or_b32_e32 v56, s4, v108
	v_ashrrev_i32_e32 v57, 31, v56
	v_lshl_add_u64 v[40:41], v[56:57], 3, s[38:39]
	global_load_dwordx2 v[42:43], v[40:41], off offset:1024
	global_load_dwordx2 v[38:39], v[40:41], off offset:1152
	global_load_dwordx2 v[36:37], v[40:41], off offset:1280
	s_nop 0
	global_load_dwordx2 v[40:41], v[40:41], off offset:1408
	v_ashrrev_i32_e32 v0, 1, v226
	v_and_b32_e32 v0, -8, v0
	v_add_u32_e32 v34, s21, v0
	s_waitcnt vmcnt(3)
	v_ffbh_u32_e32 v0, v43
	v_min_u32_e32 v0, 32, v0
	v_lshlrev_b64 v[42:43], v0, v[42:43]
	v_min_u32_e32 v35, 1, v42
	v_or_b32_e32 v35, v43, v35
	v_cvt_f32_u32_e32 v35, v35
	v_sub_u32_e32 v0, 32, v0
	v_ldexp_f32 v0, v35, v0
	v_mul_f32_e32 v0, 0x33800000, v0
	v_fmamk_f32 v0, v0, 0x3a800000, v210
	v_cmp_gt_f32_e32 vcc, s35, v0
	v_mul_f32_e32 v35, 0x4b800000, v0
	s_nop 0
	v_cndmask_b32_e32 v0, v0, v35, vcc
	v_rsq_f32_e32 v0, v0
	s_nop 0
	v_mul_f32_e32 v35, 0x45800000, v0
	v_cndmask_b32_e32 v0, v0, v35, vcc
	v_ashrrev_i32_e32 v35, 31, v34
	v_pk_mul_f32 v[84:85], v[32:33], v[0:1] op_sel_hi:[1,0]
	v_pk_mul_f32 v[44:45], v[30:31], v[0:1] op_sel_hi:[1,0]
	v_pk_mul_f32 v[72:73], v[28:29], v[0:1] op_sel_hi:[1,0]
	v_pk_mul_f32 v[42:43], v[26:27], v[0:1] op_sel_hi:[1,0]
	v_lshl_add_u64 v[26:27], v[34:35], 1, s[78:79]
	v_cmp_gt_u32_e32 vcc, 2, v108
	s_and_saveexec_b64 s[0:1], vcc
	s_cbranch_execz .LBB0_129
	v_mul_u32_u24_e32 v0, 0x1600, v108
	v_lshlrev_b32_e32 v0, 1, v0
	v_cvt_pk_bf16_f32 v28, v44, v45
	v_cvt_pk_bf16_f32 v29, v84, v85
	v_lshl_add_u64 v[32:33], v[26:27], 0, v[0:1]
	v_cvt_pk_bf16_f32 v30, v42, v43
	v_cvt_pk_bf16_f32 v31, v72, v73
	global_store_dwordx2 v[32:33], v[28:29], off offset:8
	global_store_dwordx2 v[32:33], v[30:31], off offset:264

.LBB0_135:
	s_or_b64 exec, exec, s[0:1]
	v_cmp_eq_u32_e64 s[42:43], 0, v108
	v_add_u32_e32 v96, 0x90, v56
	v_add_u32_e32 v97, 0xa0, v56
	v_add_u32_e32 v98, 0xb0, v56
	v_cndmask_b32_e64 v43, v118, v115, s[42:43]
	v_cndmask_b32_e64 v42, v117, v114, s[42:43]
	s_waitcnt vmcnt(4)
	v_pk_fma_f32 v[44:45], v[28:29], v[94:95], v[40:41] op_sel:[0,1,0] op_sel_hi:[1,0,1]
	v_cndmask_b32_e64 v47, v116, v113, s[42:43]
	v_cndmask_b32_e64 v46, v57, v112, s[42:43]
	v_pk_fma_f32 v[56:57], v[26:27], v[92:93], v[38:39] op_sel:[0,1,0] op_sel_hi:[1,0,1]
	v_pk_fma_f32 v[42:43], v[32:33], v[42:43], v[44:45]
	v_pk_fma_f32 v[46:47], v[30:31], v[46:47], v[56:57]
	v_pk_fma_f32 v[42:43], v[68:69], v[36:37], v[42:43]
	v_pk_fma_f32 v[46:47], v[64:65], v[34:35], v[46:47]
	v_cndmask_b32_e64 v65, v115, v111, s[42:43]
	v_cndmask_b32_e64 v64, v114, v110, s[42:43]
	v_pk_fma_f32 v[68:69], v[28:29], v[106:107], v[40:41] op_sel:[0,1,0] op_sel_hi:[1,0,1]
	v_cndmask_b32_e64 v81, v111, v81, s[42:43]
	v_cndmask_b32_e64 v80, v110, v80, s[42:43]
	v_pk_fma_f32 v[28:29], v[28:29], v[90:91], v[40:41] op_sel:[0,1,0] op_sel_hi:[1,0,1]
	v_pk_fma_f32 v[64:65], v[32:33], v[64:65], v[68:69]
	v_pk_fma_f32 v[28:29], v[32:33], v[80:81], v[28:29]
	v_pk_fma_f32 v[64:65], v[88:89], v[36:37], v[64:65]
	v_pk_fma_f32 v[84:85], v[26:27], v[104:105], v[38:39] op_sel:[0,1,0] op_sel_hi:[1,0,1]
	v_pk_fma_f32 v[28:29], v[60:61], v[36:37], v[28:29]
	v_cndmask_b32_e64 v37, v109, v67, s[42:43]
	v_cndmask_b32_e64 v36, v0, v66, s[42:43]
	v_pk_fma_f32 v[26:27], v[26:27], v[86:87], v[38:39] op_sel:[0,1,0] op_sel_hi:[1,0,1]
	v_cndmask_b32_e64 v72, v112, v0, s[42:43]
	v_pk_fma_f32 v[26:27], v[30:31], v[36:37], v[26:27]
	v_mul_f32_e32 v32, 0xbfb8aa3b, v29
	v_pk_fma_f32 v[26:27], v[54:55], v[34:35], v[26:27]
	v_exp_f32_e32 v32, v32
	v_mul_f32_e32 v0, 0xbfb8aa3b, v27
	v_exp_f32_e32 v0, v0
	v_cndmask_b32_e64 v73, v113, v109, s[42:43]
	v_add_f32_e32 v32, 1.0, v32
	v_pk_fma_f32 v[72:73], v[30:31], v[72:73], v[84:85]
	v_add_f32_e32 v0, 1.0, v0
	v_rcp_f32_e32 v33, v32
	v_mul_f32_e32 v32, 0xbfb8aa3b, v28
	v_rcp_f32_e32 v31, v0
	v_mul_f32_e32 v0, 0xbfb8aa3b, v26
	v_exp_f32_e32 v32, v32
	v_exp_f32_e32 v0, v0
	v_pk_fma_f32 v[72:73], v[82:83], v[34:35], v[72:73]
	v_mul_f32_e32 v68, 0xbfb8aa3b, v65
	v_mul_f32_e32 v82, 0xbfb8aa3b, v73
	v_exp_f32_e32 v68, v68
	v_exp_f32_e32 v82, v82
	v_add_f32_e32 v32, 1.0, v32
	v_add_f32_e32 v0, 1.0, v0
	v_mov_b32_e32 v34, v62
	v_mov_b32_e32 v35, v62
	v_mov_b32_e32 v53, v52
	v_mov_b32_e32 v63, v62
	v_rcp_f32_e32 v32, v32
	v_rcp_f32_e32 v30, v0
	v_pk_mul_f32 v[4:5], v[4:5], v[34:35]
	v_mov_b32_e32 v34, v52
	v_mov_b32_e32 v35, v52
	v_pk_mul_f32 v[2:3], v[2:3], v[62:63]
	v_pk_mul_f32 v[8:9], v[8:9], v[34:35]
	v_pk_mul_f32 v[6:7], v[6:7], v[52:53]
	v_mov_b32_e32 v52, v1
	v_mov_b32_e32 v54, v1
	v_mov_b32_e32 v60, v1
	v_mov_b32_e32 v62, v1
	v_mov_b32_e32 v0, v1
	v_mov_b32_dpp v52, v6 row_ror:2 row_mask:0xf bank_mask:0xf
	v_mov_b32_e32 v53, v1
	v_mov_b32_dpp v54, v7 row_ror:2 row_mask:0xf bank_mask:0xf
	v_mov_b32_e32 v55, v1
	v_mov_b32_dpp v60, v8 row_ror:2 row_mask:0xf bank_mask:0xf
	v_mov_b32_e32 v61, v1
	v_mov_b32_dpp v62, v9 row_ror:2 row_mask:0xf bank_mask:0xf
	v_add_f32_e32 v68, 1.0, v68
	v_add_f32_e32 v82, 1.0, v82
	v_mov_b32_dpp v0, v6 row_ror:1 row_mask:0xf bank_mask:0xf
	v_mov_b32_dpp v53, v7 row_ror:1 row_mask:0xf bank_mask:0xf
	v_mov_b32_dpp v55, v8 row_ror:1 row_mask:0xf bank_mask:0xf
	v_mov_b32_dpp v61, v9 row_ror:1 row_mask:0xf bank_mask:0xf
	v_cndmask_b32_e32 v34, v76, v52, vcc
	v_cndmask_b32_e32 v35, v77, v54, vcc
	v_cndmask_b32_e32 v36, v78, v60, vcc
	v_cndmask_b32_e32 v37, v79, v62, vcc
	v_rcp_f32_e32 v69, v68
	v_mul_f32_e32 v68, 0xbfb8aa3b, v64
	v_rcp_f32_e32 v83, v82
	v_mul_f32_e32 v82, 0xbfb8aa3b, v72
	v_cndmask_b32_e64 v38, v0, v70, s[42:43]
	v_cndmask_b32_e64 v39, v53, v71, s[42:43]
	v_cndmask_b32_e64 v40, v55, v74, s[42:43]
	v_cndmask_b32_e64 v41, v61, v75, s[42:43]
	v_pk_mul_f32 v[26:27], v[26:27], v[30:31]
	v_pk_mul_f32 v[28:29], v[28:29], v[32:33]
	s_waitcnt vmcnt(1)
	v_pk_fma_f32 v[30:31], v[20:21], v[36:37], v[24:25]
	v_pk_fma_f32 v[32:33], v[18:19], v[34:35], v[22:23]
	v_exp_f32_e32 v68, v68
	v_exp_f32_e32 v82, v82
	v_pk_fma_f32 v[30:31], v[16:17], v[40:41], v[30:31]
	v_pk_fma_f32 v[32:33], v[14:15], v[38:39], v[32:33]
	v_pk_fma_f32 v[8:9], v[8:9], v[12:13], v[30:31]
	v_pk_fma_f32 v[6:7], v[6:7], v[10:11], v[32:33]
	v_mul_f32_e32 v44, 0xbfb8aa3b, v43
	v_mul_f32_e32 v56, 0xbfb8aa3b, v47
	v_pk_mul_f32 v[8:9], v[28:29], v[8:9]
	v_pk_mul_f32 v[6:7], v[26:27], v[6:7]
	v_exp_f32_e32 v44, v44
	v_exp_f32_e32 v56, v56
	v_cvt_pk_bf16_f32 v6, v6, v7
	v_cvt_pk_bf16_f32 v7, v8, v9
	v_mov_b64_e32 v[8:9], s[36:37]
	v_add_f32_e32 v68, 1.0, v68
	v_add_f32_e32 v82, 1.0, v82
	v_mad_i64_i32 v[26:27], s[0:1], v96, s46, v[8:9]
	v_lshlrev_b64 v[28:29], 1, v[58:59]
	v_mov_b32_e32 v39, v1
	v_mov_b32_e32 v41, v1
	v_mov_b32_e32 v59, v1
	v_mov_b32_e32 v66, v1
	v_rcp_f32_e32 v68, v68
	v_rcp_f32_e32 v82, v82
	v_lshl_add_u64 v[26:27], v[26:27], 0, v[28:29]
	v_mov_b32_e32 v38, v1
	v_mov_b32_dpp v39, v2 row_ror:2 row_mask:0xf bank_mask:0xf
	v_mov_b32_e32 v40, v1
	v_mov_b32_dpp v41, v3 row_ror:2 row_mask:0xf bank_mask:0xf
	v_mov_b32_e32 v58, v1
	v_mov_b32_dpp v59, v4 row_ror:2 row_mask:0xf bank_mask:0xf
	v_mov_b32_e32 v63, v1
	v_mov_b32_dpp v66, v5 row_ror:2 row_mask:0xf bank_mask:0xf
	global_store_dwordx2 v[26:27], v[6:7], off
	v_mov_b32_dpp v38, v2 row_ror:1 row_mask:0xf bank_mask:0xf
	v_mov_b32_dpp v40, v3 row_ror:1 row_mask:0xf bank_mask:0xf
	v_mov_b32_dpp v58, v4 row_ror:1 row_mask:0xf bank_mask:0xf
	v_mov_b32_dpp v63, v5 row_ror:1 row_mask:0xf bank_mask:0xf
	v_cndmask_b32_e32 v6, v52, v39, vcc
	v_cndmask_b32_e32 v7, v54, v41, vcc
	v_cndmask_b32_e32 v26, v60, v59, vcc
	v_cndmask_b32_e32 v27, v62, v66, vcc
	v_add_f32_e32 v44, 1.0, v44
	v_add_f32_e32 v56, 1.0, v56
	v_cndmask_b32_e64 v30, v38, v0, s[42:43]
	v_cndmask_b32_e64 v31, v40, v53, s[42:43]
	v_cndmask_b32_e64 v32, v58, v55, s[42:43]
	v_cndmask_b32_e64 v33, v63, v61, s[42:43]
	v_pk_fma_f32 v[26:27], v[20:21], v[26:27], v[24:25]
	v_pk_fma_f32 v[6:7], v[18:19], v[6:7], v[22:23]
	v_rcp_f32_e32 v45, v44
	v_mul_f32_e32 v44, 0xbfb8aa3b, v42
	v_rcp_f32_e32 v57, v56
	v_mul_f32_e32 v56, 0xbfb8aa3b, v46
	v_pk_fma_f32 v[26:27], v[16:17], v[32:33], v[26:27]
	v_pk_fma_f32 v[6:7], v[14:15], v[30:31], v[6:7]
	v_exp_f32_e32 v44, v44
	v_exp_f32_e32 v56, v56
	v_pk_mul_f32 v[34:35], v[72:73], v[82:83]
	v_pk_mul_f32 v[36:37], v[64:65], v[68:69]
	v_pk_fma_f32 v[4:5], v[4:5], v[12:13], v[26:27]
	v_pk_fma_f32 v[2:3], v[2:3], v[10:11], v[6:7]
	v_pk_mul_f32 v[4:5], v[36:37], v[4:5]
	v_pk_mul_f32 v[2:3], v[34:35], v[2:3]
	v_add_f32_e32 v44, 1.0, v44
	v_cvt_pk_bf16_f32 v2, v2, v3
	v_cvt_pk_bf16_f32 v3, v4, v5
	v_mad_i64_i32 v[4:5], s[0:1], v97, s46, v[8:9]
	v_lshl_add_u64 v[4:5], v[4:5], 0, v[28:29]
	v_add_f32_e32 v56, 1.0, v56
	global_store_dwordx2 v[4:5], v[2:3], off
	v_mov_b32_e32 v2, v1
	v_mov_b32_e32 v3, v1
	v_mov_b32_e32 v4, v1
	v_mov_b32_e32 v5, v1
	v_rcp_f32_e32 v44, v44
	v_rcp_f32_e32 v56, v56
	v_mov_b32_e32 v0, v1
	v_mov_b32_dpp v2, v50 row_ror:2 row_mask:0xf bank_mask:0xf
	v_mov_b32_e32 v7, v1
	v_mov_b32_dpp v3, v51 row_ror:2 row_mask:0xf bank_mask:0xf
	v_mov_b32_e32 v26, v1
	v_mov_b32_dpp v4, v48 row_ror:2 row_mask:0xf bank_mask:0xf
	v_mov_b32_e32 v27, v1
	v_mov_b32_dpp v5, v49 row_ror:2 row_mask:0xf bank_mask:0xf
	v_mov_b32_dpp v0, v50 row_ror:1 row_mask:0xf bank_mask:0xf
	v_mov_b32_dpp v7, v51 row_ror:1 row_mask:0xf bank_mask:0xf
	v_mov_b32_dpp v26, v48 row_ror:1 row_mask:0xf bank_mask:0xf
	v_mov_b32_dpp v27, v49 row_ror:1 row_mask:0xf bank_mask:0xf
	v_cndmask_b32_e32 v2, v39, v2, vcc
	v_cndmask_b32_e32 v3, v41, v3, vcc
	v_cndmask_b32_e32 v4, v59, v4, vcc
	v_cndmask_b32_e32 v5, v66, v5, vcc
	v_cndmask_b32_e64 v6, v0, v38, s[42:43]
	v_cndmask_b32_e64 v7, v7, v40, s[42:43]
	v_cndmask_b32_e64 v26, v26, v58, s[42:43]
	v_cndmask_b32_e64 v27, v27, v63, s[42:43]
	v_pk_fma_f32 v[2:3], v[18:19], v[2:3], v[22:23]
	v_pk_fma_f32 v[4:5], v[20:21], v[4:5], v[24:25]
	v_pk_fma_f32 v[2:3], v[14:15], v[6:7], v[2:3]
	v_pk_fma_f32 v[4:5], v[16:17], v[26:27], v[4:5]
	v_pk_mul_f32 v[30:31], v[46:47], v[56:57]
	v_pk_mul_f32 v[32:33], v[42:43], v[44:45]
	v_pk_fma_f32 v[2:3], v[50:51], v[10:11], v[2:3]
	v_pk_fma_f32 v[4:5], v[48:49], v[12:13], v[4:5]
	v_pk_mul_f32 v[2:3], v[30:31], v[2:3]
	v_pk_mul_f32 v[4:5], v[32:33], v[4:5]
	v_cvt_pk_bf16_f32 v2, v2, v3
	s_nop 0
	v_cvt_pk_bf16_f32 v3, v4, v5
	v_mad_i64_i32 v[4:5], s[0:1], v98, s46, v[8:9]
	v_lshl_add_u64 v[4:5], v[4:5], 0, v[28:29]
	global_store_dwordx2 v[4:5], v[2:3], off
	s_andn2_b64 vcc, exec, s[40:41]
	s_mov_b64 s[0:1], -1
	s_cbranch_vccnz .LBB0_102
	s_andn2_b64 vcc, exec, s[30:31]
	s_cbranch_vccnz .LBB0_101
	s_barrier
	s_branch .LBB0_101
.Lcg_skip0:
	s_waitcnt vmcnt(0)
	s_branch .LBB0_115
